# ple epilogue: 14 of the 16 x float4 loads hoisted (6 to start of proj gemm, 8 into its last K-step) into free VGPRs, exact vmcnt waits regenerated (on v59)
# speedup vs baseline: 1.0070x; 1.0020x over previous
; template <int NI, int NB, bool SWAP = false>
; DI void gemm_main(f32x16 (&acc0)[2][NI], f32x16 (&acc1)[2][NI], const bf16_t* __restrict__ A, int lda,
;                   const bf16_t* __restrict__ B0, const bf16_t* __restrict__ B1, int ldb, int K, char* lds) {
;     ...
;   const int lr = tid >> 3, lc = (tid & 7) * 8;
;   u32x4 ra[4], rb0[2 * NI], rb1[2 * NI];
;   const char* Ab = (const char*)A;
;   const char* B0b = (const char*)B0;
;   const char* B1b = (NB == 2) ? (const char*)B1 : (const char*)B0;
;   const unsigned aoff = (unsigned)(lr * lda + lc) * 2u, boff = (unsigned)(lr * ldb + lc) * 2u;
;   const unsigned astep = (unsigned)(32 * lda) * 2u, bstep = (unsigned)(32 * ldb) * 2u;
; #pragma unroll
;   for (int i = 0; i < 4; ++i) ra[i] = *(const u32x4*)(Ab + (aoff + astep * i));
; #pragma unroll
;   for (int i = 0; i < 2 * NI; ++i) {
;     rb0[i] = *(const u32x4*)(B0b + (boff + bstep * i));
;     if (NB == 2) rb1[i] = *(const u32x4*)(B1b + (boff + bstep * i));
;   }
;   for (int k0 = 0; k0 < K; k0 += 64) {
;     __syncthreads();
; #pragma unroll
;     for (int i = 0; i < 4; ++i) *(u32x4*)(As + (lr + 32 * i) * 72 + lc) = ra[i];
; #pragma unroll
;     for (int i = 0; i < 2 * NI; ++i) {
;       *(u32x4*)(B0s + (lr + 32 * i) * 72 + lc) = rb0[i];
;       if (NB == 2) *(u32x4*)(B1s + (lr + 32 * i) * 72 + lc) = rb1[i];
;     }
;     if (k0 + 64 < K) {
;       const unsigned kb = (unsigned)(k0 + 64) * 2u;
; #pragma unroll
;       for (int i = 0; i < 4; ++i) ra[i] = *(const u32x4*)(Ab + (aoff + astep * i + kb));
; #pragma unroll
;       for (int i = 0; i < 2 * NI; ++i) {
;         rb0[i] = *(const u32x4*)(B0b + (boff + bstep * i + kb));
;         if (NB == 2) rb1[i] = *(const u32x4*)(B1b + (boff + bstep * i + kb));
;       }
;     }
;     __syncthreads();
; DI void phase_ple(const bf16_t* __restrict__ Nb, const bf16_t* __restrict__ PB, const bf16_t* __restrict__ PG,
;                           const bf16_t* __restrict__ PP, float* __restrict__ x, char* lds) {
;     ...
;         float* xp = x + (size_t)(mt * 128 + 64 * wm + 32 * mi + l31) * 1024 + nt * 128 + 64 * wn + 32 * ni + 4 * h2;
;         float4 xs[4];
; #pragma unroll
;         for (int g = 0; g < 4; ++g) xs[g] = *(const float4*)(xp + 8 * g);
.LBB0_1286:
	s_lshl_b64 s[6:7], s[28:29], 16
	v_mov_b32 v0, 0
	s_add_u32 s24, s38, s6
	v_add_u32_e32 v98, v0, v210
	v_lshlrev_b32_e32 v0, 4, v98
	s_addc_u32 s25, s39, s7
	s_lshl_b32 s6, s49, 16
	v_ashrrev_i32_e32 v99, 3, v98
	v_and_b32_e32 v100, 0x70, v0
	s_add_u32 s6, s42, s6
	v_lshl_or_b32 v152, v99, 9, v100
	s_addc_u32 s7, s43, 0
	v_add_u32_e32 v0, 0x4000, v152
	s_waitcnt vmcnt(1)
	v_add_u32_e32 v58, 0x8000, v152
	s_waitcnt vmcnt(0)
	v_add_u32_e32 v62, 0xc000, v152
	global_load_dwordx4 v[18:21], v152, s[24:25]
	global_load_dwordx4 v[30:33], v62, s[24:25]
	global_load_dwordx4 v[22:25], v0, s[24:25]
	global_load_dwordx4 v[26:29], v58, s[24:25]
	global_load_dwordx4 v[50:53], v152, s[6:7]
	global_load_dwordx4 v[54:57], v0, s[6:7]
	s_nop 0
	global_load_dwordx4 v[58:61], v58, s[6:7]
	s_nop 0
	global_load_dwordx4 v[62:65], v62, s[6:7]
	s_lshl_b32 s100, s49, 9
	s_mov_b32 s101, 0
	v_lshl_add_u32 v208, s28, 7, v150
	v_ashrrev_i32_e32 v209, 31, v208
	v_lshlrev_b64 v[208:209], 12, v[208:209]
	v_lshl_add_u64 v[182:183], v[146:147], 0, s[100:101]
	v_lshl_add_u64 v[182:183], v[182:183], 0, v[208:209]
	s_mov_b32 s100, 0x20000
	v_lshl_add_u64 v[208:209], v[182:183], 0, s[100:101]
	global_load_dwordx4 v[184:187], v[182:183], off
	global_load_dwordx4 v[188:191], v[182:183], off offset:32
	global_load_dwordx4 v[192:195], v[182:183], off offset:64
	global_load_dwordx4 v[196:199], v[182:183], off offset:96
	global_load_dwordx4 v[200:203], v[182:183], off offset:128
	global_load_dwordx4 v[204:207], v[182:183], off offset:160
	v_mul_lo_u32 v99, v99, s12
	v_add3_u32 v151, 16, v100, v99
	s_barrier
	v_and_b32_e32 v101, 31, v98
	v_lshrrev_b32_e32 v0, 1, v98
	v_and_or_b32 v101, v0, s11, v101
	v_and_b32_e32 v0, 16, v0
	v_add_u32_e32 v0, 16, v0
	v_and_b32_e32 v98, 0x5f, v98
	v_mad_u64_u32 v[148:149], s[34:35], v101, s12, v[0:1]
	v_mad_u32_u24 v0, v98, s12, v0
	s_waitcnt vmcnt(13)
	ds_write_b128 v151, v[18:21]
	s_waitcnt vmcnt(11)
	ds_write_b128 v151, v[22:25] offset:4608
	s_waitcnt vmcnt(10)
	ds_write_b128 v151, v[26:29] offset:9216
	ds_write_b128 v151, v[30:33] offset:13824
	s_waitcnt vmcnt(9)
	ds_write_b128 v151, v[50:53] offset:18432
	s_waitcnt vmcnt(8)
	ds_write_b128 v151, v[54:57] offset:23040
	s_waitcnt vmcnt(7)
	ds_write_b128 v151, v[58:61] offset:27648
	s_waitcnt vmcnt(6)
	ds_write_b128 v151, v[62:65] offset:32256
	v_add_u32_e32 v18, 0x4080, v152
	v_add_u32_e32 v19, 0x8080, v152
	v_add_u32_e32 v20, 0xc080, v152
	global_load_dwordx4 v[130:133], v152, s[24:25] offset:128
	global_load_dwordx4 v[134:137], v18, s[24:25]
	global_load_dwordx4 v[138:141], v19, s[24:25]
	global_load_dwordx4 v[154:157], v20, s[24:25]
	global_load_dwordx4 v[142:145], v20, s[6:7]
	global_load_dwordx4 v[158:161], v19, s[6:7]
	global_load_dwordx4 v[162:165], v18, s[6:7]
	global_load_dwordx4 v[166:169], v152, s[6:7] offset:128
	s_waitcnt lgkmcnt(0)
	s_barrier
	s_setprio 1
	ds_read_b128 v[18:21], v0 offset:18432
	ds_read_b128 v[22:25], v148
	ds_read_b128 v[26:29], v0 offset:23040
	s_waitcnt lgkmcnt(1)
	v_mfma_f32_32x32x16_bf16 v[114:129], v[18:21], v[22:25], 0
	s_waitcnt lgkmcnt(0)
	v_mfma_f32_32x32x16_bf16 v[98:113], v[26:29], v[22:25], 0
	ds_read_b128 v[22:25], v148 offset:4608
	ds_read_b128 v[170:173], v0 offset:18464
	ds_read_b128 v[174:177], v148 offset:32
	ds_read_b128 v[178:181], v0 offset:23072
	s_waitcnt lgkmcnt(3)
	v_mfma_f32_32x32x16_bf16 v[50:65], v[18:21], v[22:25], 0
	v_mfma_f32_32x32x16_bf16 v[18:33], v[26:29], v[22:25], 0
	s_waitcnt lgkmcnt(1)
	v_mfma_f32_32x32x16_bf16 v[114:129], v[170:173], v[174:177], v[114:129]
	s_waitcnt lgkmcnt(0)
	v_mfma_f32_32x32x16_bf16 v[98:113], v[178:181], v[174:177], v[98:113]
	ds_read_b128 v[174:177], v148 offset:4640
	s_waitcnt lgkmcnt(0)
	v_mfma_f32_32x32x16_bf16 v[50:65], v[170:173], v[174:177], v[50:65]
	v_mfma_f32_32x32x16_bf16 v[18:33], v[178:181], v[174:177], v[18:33]
	ds_read_b128 v[170:173], v0 offset:18496
	ds_read_b128 v[174:177], v148 offset:64
	ds_read_b128 v[178:181], v0 offset:23104
	s_waitcnt lgkmcnt(1)
	v_mfma_f32_32x32x16_bf16 v[114:129], v[170:173], v[174:177], v[114:129]
	s_waitcnt lgkmcnt(0)
	v_mfma_f32_32x32x16_bf16 v[98:113], v[178:181], v[174:177], v[98:113]
	ds_read_b128 v[174:177], v148 offset:4672
	s_waitcnt lgkmcnt(0)
	v_mfma_f32_32x32x16_bf16 v[50:65], v[170:173], v[174:177], v[50:65]
	v_mfma_f32_32x32x16_bf16 v[18:33], v[178:181], v[174:177], v[18:33]
	ds_read_b128 v[170:173], v0 offset:18528
	ds_read_b128 v[174:177], v148 offset:96
	ds_read_b128 v[178:181], v0 offset:23136
	s_waitcnt lgkmcnt(1)
	v_mfma_f32_32x32x16_bf16 v[114:129], v[170:173], v[174:177], v[114:129]
	s_waitcnt lgkmcnt(0)
	v_mfma_f32_32x32x16_bf16 v[98:113], v[178:181], v[174:177], v[98:113]
	ds_read_b128 v[174:177], v148 offset:4704
	s_waitcnt lgkmcnt(0)
	v_mfma_f32_32x32x16_bf16 v[50:65], v[170:173], v[174:177], v[50:65]
	v_mfma_f32_32x32x16_bf16 v[18:33], v[178:181], v[174:177], v[18:33]
	s_setprio 0
	s_barrier
	s_waitcnt vmcnt(7)
	ds_write_b128 v151, v[130:133]
	s_waitcnt vmcnt(6)
	ds_write_b128 v151, v[134:137] offset:4608
	s_waitcnt vmcnt(5)
	ds_write_b128 v151, v[138:141] offset:9216
	s_waitcnt vmcnt(4)
	ds_write_b128 v151, v[154:157] offset:13824
	s_waitcnt vmcnt(0)
	ds_write_b128 v151, v[166:169] offset:18432
	ds_write_b128 v151, v[162:165] offset:23040
	ds_write_b128 v151, v[158:161] offset:27648
	ds_write_b128 v151, v[142:145] offset:32256
	v_add_u32_e32 v149, 0x4100, v152
	v_add_u32_e32 v153, 0x8100, v152
	v_add_u32_e32 v154, 0xc100, v152
	global_load_dwordx4 v[130:133], v152, s[24:25] offset:256
	global_load_dwordx4 v[134:137], v149, s[24:25]
	global_load_dwordx4 v[138:141], v153, s[24:25]
	global_load_dwordx4 v[142:145], v154, s[24:25]
	s_nop 0
	global_load_dwordx4 v[154:157], v154, s[6:7]
	s_nop 0
	global_load_dwordx4 v[158:161], v153, s[6:7]
	global_load_dwordx4 v[162:165], v149, s[6:7]
	global_load_dwordx4 v[166:169], v152, s[6:7] offset:256
	s_waitcnt lgkmcnt(0)
	s_barrier
; #define MFMA32(a, b, c) __builtin_amdgcn_mfma_f32_32x32x16_bf16((a), (b), (c), 0, 0, 0)
; template <int NI, int NB, bool SWAP = false>
; DI void gemm_main(f32x16 (&acc0)[2][NI], f32x16 (&acc1)[2][NI], const bf16_t* __restrict__ A, int lda,
;                   const bf16_t* __restrict__ B0, const bf16_t* __restrict__ B1, int ldb, int K, char* lds) {
;     ...
;   for (int k0 = 0; k0 < K; k0 += 64) {
;     __syncthreads();
; #pragma unroll
;     for (int i = 0; i < 4; ++i) *(u32x4*)(As + (lr + 32 * i) * 72 + lc) = ra[i];
; #pragma unroll
;     for (int i = 0; i < 2 * NI; ++i) {
;       *(u32x4*)(B0s + (lr + 32 * i) * 72 + lc) = rb0[i];
;       if (NB == 2) *(u32x4*)(B1s + (lr + 32 * i) * 72 + lc) = rb1[i];
;     }
;     if (k0 + 64 < K) {
;       const unsigned kb = (unsigned)(k0 + 64) * 2u;
; #pragma unroll
;       for (int i = 0; i < 4; ++i) ra[i] = *(const u32x4*)(Ab + (aoff + astep * i + kb));
; #pragma unroll
;       for (int i = 0; i < 2 * NI; ++i) {
;         rb0[i] = *(const u32x4*)(B0b + (boff + bstep * i + kb));
;         if (NB == 2) rb1[i] = *(const u32x4*)(B1b + (boff + bstep * i + kb));
;       }
;     }
;     __syncthreads();
;     __builtin_amdgcn_s_setprio(1);
; #pragma unroll
;     for (int ks = 0; ks < 4; ++ks) {
;       bf16x8 af[2], bf0[NI], bf1[NI];
; #pragma unroll
;       for (int mi = 0; mi < 2; ++mi) af[mi] = *(const bf16x8*)(As + (64 * wm + 32 * mi + l31) * 72 + 16 * ks + 8 * h2);
; #pragma unroll
;       for (int ni = 0; ni < NI; ++ni) {
;         bf0[ni] = *(const bf16x8*)(B0s + (32 * NI * wn + 32 * ni + l31) * 72 + 16 * ks + 8 * h2);
;         if (NB == 2) bf1[ni] = *(const bf16x8*)(B1s + (32 * NI * wn + 32 * ni + l31) * 72 + 16 * ks + 8 * h2);
;       }
; #pragma unroll
;       for (int mi = 0; mi < 2; ++mi)
; #pragma unroll
;         for (int ni = 0; ni < NI; ++ni) {
;           acc0[mi][ni] = SWAP ? MFMA32(bf0[ni], af[mi], acc0[mi][ni]) : MFMA32(af[mi], bf0[ni], acc0[mi][ni]);
;           if (NB == 2) acc1[mi][ni] = SWAP ? MFMA32(bf1[ni], af[mi], acc1[mi][ni]) : MFMA32(af[mi], bf1[ni], acc1[mi][ni]);
;         }
;     }
;     __builtin_amdgcn_s_setprio(0);
;   }
	s_setprio 1
	ds_read_b128 v[170:173], v0 offset:18432
	ds_read_b128 v[174:177], v148
	ds_read_b128 v[178:181], v0 offset:23040
	s_waitcnt lgkmcnt(1)
	v_mfma_f32_32x32x16_bf16 v[114:129], v[170:173], v[174:177], v[114:129]
	s_waitcnt lgkmcnt(0)
	v_mfma_f32_32x32x16_bf16 v[98:113], v[178:181], v[174:177], v[98:113]
	ds_read_b128 v[174:177], v148 offset:4608
	s_waitcnt lgkmcnt(0)
	v_mfma_f32_32x32x16_bf16 v[50:65], v[170:173], v[174:177], v[50:65]
	v_mfma_f32_32x32x16_bf16 v[18:33], v[178:181], v[174:177], v[18:33]
	ds_read_b128 v[170:173], v0 offset:18464
	ds_read_b128 v[174:177], v148 offset:32
	ds_read_b128 v[178:181], v0 offset:23072
	s_waitcnt lgkmcnt(1)
	v_mfma_f32_32x32x16_bf16 v[114:129], v[170:173], v[174:177], v[114:129]
	s_waitcnt lgkmcnt(0)
	v_mfma_f32_32x32x16_bf16 v[98:113], v[178:181], v[174:177], v[98:113]
	ds_read_b128 v[174:177], v148 offset:4640
	s_waitcnt lgkmcnt(0)
	v_mfma_f32_32x32x16_bf16 v[50:65], v[170:173], v[174:177], v[50:65]
	v_mfma_f32_32x32x16_bf16 v[18:33], v[178:181], v[174:177], v[18:33]
	ds_read_b128 v[170:173], v0 offset:18496
	ds_read_b128 v[174:177], v148 offset:64
	ds_read_b128 v[178:181], v0 offset:23104
	s_waitcnt lgkmcnt(1)
	v_mfma_f32_32x32x16_bf16 v[114:129], v[170:173], v[174:177], v[114:129]
	s_waitcnt lgkmcnt(0)
	v_mfma_f32_32x32x16_bf16 v[98:113], v[178:181], v[174:177], v[98:113]
	ds_read_b128 v[174:177], v148 offset:4672
	s_waitcnt lgkmcnt(0)
	v_mfma_f32_32x32x16_bf16 v[50:65], v[170:173], v[174:177], v[50:65]
	v_mfma_f32_32x32x16_bf16 v[18:33], v[178:181], v[174:177], v[18:33]
	ds_read_b128 v[170:173], v0 offset:18528
	ds_read_b128 v[174:177], v148 offset:96
	ds_read_b128 v[178:181], v0 offset:23136
	s_waitcnt lgkmcnt(1)
	v_mfma_f32_32x32x16_bf16 v[114:129], v[170:173], v[174:177], v[114:129]
	s_waitcnt lgkmcnt(0)
	v_mfma_f32_32x32x16_bf16 v[98:113], v[178:181], v[174:177], v[98:113]
	ds_read_b128 v[174:177], v148 offset:4704
	s_waitcnt lgkmcnt(0)
	v_mfma_f32_32x32x16_bf16 v[50:65], v[170:173], v[174:177], v[50:65]
	v_mfma_f32_32x32x16_bf16 v[18:33], v[178:181], v[174:177], v[18:33]
	s_setprio 0
	s_barrier
	s_waitcnt vmcnt(7)
	ds_write_b128 v151, v[130:133]
	s_waitcnt vmcnt(6)
	ds_write_b128 v151, v[134:137] offset:4608
	s_waitcnt vmcnt(5)
	ds_write_b128 v151, v[138:141] offset:9216
	s_waitcnt vmcnt(4)
	ds_write_b128 v151, v[142:145] offset:13824
	s_waitcnt vmcnt(0)
	ds_write_b128 v151, v[166:169] offset:18432
	ds_write_b128 v151, v[162:165] offset:23040
	ds_write_b128 v151, v[158:161] offset:27648
	ds_write_b128 v151, v[154:157] offset:32256
	v_add_u32_e32 v149, 0x4180, v152
	v_add_u32_e32 v153, 0x8180, v152
	v_add_u32_e32 v154, 0xc180, v152
	global_load_dwordx4 v[130:133], v152, s[24:25] offset:384
	global_load_dwordx4 v[134:137], v149, s[24:25]
	global_load_dwordx4 v[138:141], v153, s[24:25]
	global_load_dwordx4 v[142:145], v154, s[24:25]
	s_nop 0
	global_load_dwordx4 v[154:157], v154, s[6:7]
	s_nop 0
	global_load_dwordx4 v[158:161], v153, s[6:7]
	global_load_dwordx4 v[162:165], v149, s[6:7]
	global_load_dwordx4 v[166:169], v152, s[6:7] offset:384
	s_waitcnt lgkmcnt(0)
	s_barrier
	s_setprio 1
	ds_read_b128 v[170:173], v0 offset:18432
	ds_read_b128 v[174:177], v148
	ds_read_b128 v[178:181], v0 offset:23040
	s_waitcnt lgkmcnt(1)
	v_mfma_f32_32x32x16_bf16 v[114:129], v[170:173], v[174:177], v[114:129]
	s_waitcnt lgkmcnt(0)
	v_mfma_f32_32x32x16_bf16 v[98:113], v[178:181], v[174:177], v[98:113]
	ds_read_b128 v[174:177], v148 offset:4608
	s_waitcnt lgkmcnt(0)
	v_mfma_f32_32x32x16_bf16 v[50:65], v[170:173], v[174:177], v[50:65]
	v_mfma_f32_32x32x16_bf16 v[18:33], v[178:181], v[174:177], v[18:33]
	ds_read_b128 v[170:173], v0 offset:18464
	ds_read_b128 v[174:177], v148 offset:32
	ds_read_b128 v[178:181], v0 offset:23072
	s_waitcnt lgkmcnt(1)
	v_mfma_f32_32x32x16_bf16 v[114:129], v[170:173], v[174:177], v[114:129]
	s_waitcnt lgkmcnt(0)
	v_mfma_f32_32x32x16_bf16 v[98:113], v[178:181], v[174:177], v[98:113]
	ds_read_b128 v[174:177], v148 offset:4640
	s_waitcnt lgkmcnt(0)
	v_mfma_f32_32x32x16_bf16 v[50:65], v[170:173], v[174:177], v[50:65]
	v_mfma_f32_32x32x16_bf16 v[18:33], v[178:181], v[174:177], v[18:33]
	ds_read_b128 v[170:173], v0 offset:18496
	ds_read_b128 v[174:177], v148 offset:64
	ds_read_b128 v[178:181], v0 offset:23104
	s_waitcnt lgkmcnt(1)
	v_mfma_f32_32x32x16_bf16 v[114:129], v[170:173], v[174:177], v[114:129]
	s_waitcnt lgkmcnt(0)
	v_mfma_f32_32x32x16_bf16 v[98:113], v[178:181], v[174:177], v[98:113]
	ds_read_b128 v[174:177], v148 offset:4672
	s_waitcnt lgkmcnt(0)
	v_mfma_f32_32x32x16_bf16 v[50:65], v[170:173], v[174:177], v[50:65]
	v_mfma_f32_32x32x16_bf16 v[18:33], v[178:181], v[174:177], v[18:33]
	ds_read_b128 v[170:173], v0 offset:18528
	ds_read_b128 v[174:177], v148 offset:96
	ds_read_b128 v[178:181], v0 offset:23136
	s_waitcnt lgkmcnt(1)
	v_mfma_f32_32x32x16_bf16 v[114:129], v[170:173], v[174:177], v[114:129]
	s_waitcnt lgkmcnt(0)
	v_mfma_f32_32x32x16_bf16 v[98:113], v[178:181], v[174:177], v[98:113]
	ds_read_b128 v[174:177], v148 offset:4704
	s_waitcnt lgkmcnt(0)
	v_mfma_f32_32x32x16_bf16 v[50:65], v[170:173], v[174:177], v[50:65]
	v_mfma_f32_32x32x16_bf16 v[18:33], v[178:181], v[174:177], v[18:33]
	s_setprio 0
	s_barrier
	s_waitcnt vmcnt(7)
	ds_write_b128 v151, v[130:133]
	s_waitcnt vmcnt(6)
	ds_write_b128 v151, v[134:137] offset:4608
	s_waitcnt vmcnt(5)
	ds_write_b128 v151, v[138:141] offset:9216
	s_waitcnt vmcnt(4)
	ds_write_b128 v151, v[142:145] offset:13824
	s_waitcnt vmcnt(0)
	ds_write_b128 v151, v[166:169] offset:18432
	ds_write_b128 v151, v[162:165] offset:23040
	ds_write_b128 v151, v[158:161] offset:27648
	ds_write_b128 v151, v[154:157] offset:32256
	s_waitcnt lgkmcnt(0)
	s_barrier
; #define MFMA32(a, b, c) __builtin_amdgcn_mfma_f32_32x32x16_bf16((a), (b), (c), 0, 0, 0)
; DI float sigmoidf_(float x) { return __builtin_amdgcn_rcpf(1.f + __expf(-x)); }
; template <int NI, int NB, bool SWAP = false>
; DI void gemm_main(f32x16 (&acc0)[2][NI], f32x16 (&acc1)[2][NI], const bf16_t* __restrict__ A, int lda,
;                   const bf16_t* __restrict__ B0, const bf16_t* __restrict__ B1, int ldb, int K, char* lds) {
;     ...
; #pragma unroll
;     for (int ks = 0; ks < 4; ++ks) {
;       bf16x8 af[2], bf0[NI], bf1[NI];
; #pragma unroll
;       for (int mi = 0; mi < 2; ++mi) af[mi] = *(const bf16x8*)(As + (64 * wm + 32 * mi + l31) * 72 + 16 * ks + 8 * h2);
; #pragma unroll
;       for (int ni = 0; ni < NI; ++ni) {
;         bf0[ni] = *(const bf16x8*)(B0s + (32 * NI * wn + 32 * ni + l31) * 72 + 16 * ks + 8 * h2);
;         if (NB == 2) bf1[ni] = *(const bf16x8*)(B1s + (32 * NI * wn + 32 * ni + l31) * 72 + 16 * ks + 8 * h2);
;       }
; #pragma unroll
;       for (int mi = 0; mi < 2; ++mi)
; #pragma unroll
;         for (int ni = 0; ni < NI; ++ni) {
;           acc0[mi][ni] = SWAP ? MFMA32(bf0[ni], af[mi], acc0[mi][ni]) : MFMA32(af[mi], bf0[ni], acc0[mi][ni]);
;           if (NB == 2) acc1[mi][ni] = SWAP ? MFMA32(bf1[ni], af[mi], acc1[mi][ni]) : MFMA32(af[mi], bf1[ni], acc1[mi][ni]);
;         }
;     }
;     __builtin_amdgcn_s_setprio(0);
;   }
; DI void phase_ple(const bf16_t* __restrict__ Nb, const bf16_t* __restrict__ PB, const bf16_t* __restrict__ PG,
;                           const bf16_t* __restrict__ PP, float* __restrict__ x, char* lds) {
;     ...
;         float* xp = x + (size_t)(mt * 128 + 64 * wm + 32 * mi + l31) * 1024 + nt * 128 + 64 * wn + 32 * ni + 4 * h2;
;         float4 xs[4];
; #pragma unroll
;         for (int g = 0; g < 4; ++g) xs[g] = *(const float4*)(xp + 8 * g);
; #pragma unroll
;         for (int g = 0; g < 4; ++g) {
;           float4 o;
;           o.x = xs[g].x + sigmoidf_(a0[mi][ni][4 * g]) * a1[mi][ni][4 * g];
;           o.y = xs[g].y + sigmoidf_(a0[mi][ni][4 * g + 1]) * a1[mi][ni][4 * g + 1];
;           o.z = xs[g].z + sigmoidf_(a0[mi][ni][4 * g + 2]) * a1[mi][ni][4 * g + 2];
;           o.w = xs[g].w + sigmoidf_(a0[mi][ni][4 * g + 3]) * a1[mi][ni][4 * g + 3];
;           *(float4*)(xp + 8 * g) = o;
	s_setprio 1
	ds_read_b128 v[130:133], v0 offset:18432
	ds_read_b128 v[134:137], v148
	ds_read_b128 v[138:141], v0 offset:23040
	s_waitcnt lgkmcnt(1)
	v_mfma_f32_32x32x16_bf16 v[114:129], v[130:133], v[134:137], v[114:129]
	s_waitcnt lgkmcnt(0)
	v_mfma_f32_32x32x16_bf16 v[98:113], v[138:141], v[134:137], v[98:113]
	global_load_dwordx4 v[154:157], v[182:183], off offset:192
	global_load_dwordx4 v[158:161], v[182:183], off offset:224
	global_load_dwordx4 v[162:165], v[208:209], off
	global_load_dwordx4 v[166:169], v[208:209], off offset:32
	global_load_dwordx4 v[170:173], v[208:209], off offset:64
	global_load_dwordx4 v[174:177], v[208:209], off offset:96
	global_load_dwordx4 v[178:181], v[208:209], off offset:128
	global_load_dwordx4 v[142:145], v[208:209], off offset:160
	ds_read_b128 v[134:137], v148 offset:4608
	s_waitcnt lgkmcnt(0)
	v_mfma_f32_32x32x16_bf16 v[50:65], v[130:133], v[134:137], v[50:65]
	v_mfma_f32_32x32x16_bf16 v[18:33], v[138:141], v[134:137], v[18:33]
	ds_read_b128 v[130:133], v0 offset:18464
	ds_read_b128 v[134:137], v148 offset:32
	ds_read_b128 v[138:141], v0 offset:23072
	s_waitcnt lgkmcnt(1)
	v_mfma_f32_32x32x16_bf16 v[114:129], v[130:133], v[134:137], v[114:129]
	s_waitcnt lgkmcnt(0)
	v_mfma_f32_32x32x16_bf16 v[98:113], v[138:141], v[134:137], v[98:113]
	ds_read_b128 v[134:137], v148 offset:4640
	s_waitcnt lgkmcnt(0)
	v_mfma_f32_32x32x16_bf16 v[50:65], v[130:133], v[134:137], v[50:65]
	v_mfma_f32_32x32x16_bf16 v[18:33], v[138:141], v[134:137], v[18:33]
	ds_read_b128 v[130:133], v0 offset:18496
	ds_read_b128 v[134:137], v148 offset:64
	ds_read_b128 v[138:141], v0 offset:23104
	s_waitcnt lgkmcnt(1)
	v_mfma_f32_32x32x16_bf16 v[114:129], v[130:133], v[134:137], v[114:129]
	s_waitcnt lgkmcnt(0)
	v_mfma_f32_32x32x16_bf16 v[98:113], v[138:141], v[134:137], v[98:113]
	ds_read_b128 v[134:137], v148 offset:4672
	s_waitcnt lgkmcnt(0)
	v_mfma_f32_32x32x16_bf16 v[50:65], v[130:133], v[134:137], v[50:65]
	v_mfma_f32_32x32x16_bf16 v[18:33], v[138:141], v[134:137], v[18:33]
	ds_read_b128 v[130:133], v0 offset:18528
	ds_read_b128 v[134:137], v148 offset:96
	ds_read_b128 v[138:141], v0 offset:23136
	s_waitcnt lgkmcnt(1)
	v_mfma_f32_32x32x16_bf16 v[114:129], v[130:133], v[134:137], v[114:129]
	s_waitcnt lgkmcnt(0)
	v_mfma_f32_32x32x16_bf16 v[98:113], v[138:141], v[134:137], v[98:113]
	ds_read_b128 v[134:137], v148 offset:4704
	s_waitcnt lgkmcnt(0)
	v_mfma_f32_32x32x16_bf16 v[50:65], v[130:133], v[134:137], v[50:65]
	v_mfma_f32_32x32x16_bf16 v[18:33], v[138:141], v[134:137], v[18:33]
	s_setprio 0
	v_mul_f32_e32 v0, 0xbfb8aa3b, v82
	v_exp_f32_e32 v0, v0
	v_lshl_add_u32 v132, s28, 7, v150
	s_lshl_b32 s28, s49, 9
	v_ashrrev_i32_e32 v133, 31, v132
	v_add_f32_e32 v0, 1.0, v0
	v_rcp_f32_e32 v136, v0
	v_mul_f32_e32 v0, 0xbfb8aa3b, v83
	v_exp_f32_e32 v0, v0
	v_lshl_add_u64 v[130:131], v[146:147], 0, s[28:29]
	v_lshlrev_b64 v[134:135], 12, v[132:133]
	v_lshl_add_u64 v[134:135], v[130:131], 0, v[134:135]
	v_add_f32_e32 v0, 1.0, v0
	v_rcp_f32_e32 v137, v0
	v_mul_f32_e32 v0, 0xbfb8aa3b, v84
	v_exp_f32_e32 v0, v0
	s_add_i32 s48, s48, 1
	s_mul_i32 s6, s48, s66
	s_add_i32 s6, s6, s3
	v_add_f32_e32 v0, 1.0, v0
	v_rcp_f32_e32 v138, v0
	v_mul_f32_e32 v0, 0xbfb8aa3b, v85
	v_exp_f32_e32 v0, v0
	s_lshr_b32 s7, s6, 1
	v_readlane_b32 s24, v243, 21
	s_add_i32 s28, s7, s24
	v_add_f32_e32 v0, 1.0, v0
	v_rcp_f32_e32 v139, v0
	v_mul_f32_e32 v0, 0xbfb8aa3b, v86
	v_exp_f32_e32 v0, v0
	s_cmpk_lt_u32 s6, 0x100
	v_add_f32_e32 v0, 1.0, v0
	v_rcp_f32_e32 v86, v0
	v_mul_f32_e32 v0, 0xbfb8aa3b, v87
	v_exp_f32_e32 v0, v0
	v_pk_fma_f32 v[82:83], v[136:137], v[114:115], v[184:185]
	v_pk_fma_f32 v[84:85], v[138:139], v[116:117], v[186:187]
	global_store_dwordx4 v[134:135], v[82:85], off
	v_add_f32_e32 v0, 1.0, v0
	v_rcp_f32_e32 v87, v0
	v_mul_f32_e32 v0, 0xbfb8aa3b, v88
	v_exp_f32_e32 v0, v0
	v_pk_fma_f32 v[82:83], v[86:87], v[118:119], v[188:189]
	v_add_f32_e32 v0, 1.0, v0
	v_rcp_f32_e32 v88, v0
	v_mul_f32_e32 v0, 0xbfb8aa3b, v89
	v_exp_f32_e32 v0, v0
	s_nop 0
	v_add_f32_e32 v0, 1.0, v0
	v_rcp_f32_e32 v89, v0
	v_mul_f32_e32 v0, 0xbfb8aa3b, v90
	v_exp_f32_e32 v0, v0
	v_pk_fma_f32 v[84:85], v[88:89], v[120:121], v[190:191]
	global_store_dwordx4 v[134:135], v[82:85], off offset:32
	v_add_f32_e32 v0, 1.0, v0
	v_rcp_f32_e32 v86, v0
	v_mul_f32_e32 v0, 0xbfb8aa3b, v91
	v_exp_f32_e32 v0, v0
	s_nop 0
	v_add_f32_e32 v0, 1.0, v0
	v_rcp_f32_e32 v87, v0
	v_mul_f32_e32 v0, 0xbfb8aa3b, v92
	v_exp_f32_e32 v0, v0
	v_pk_fma_f32 v[82:83], v[86:87], v[122:123], v[192:193]
	v_add_f32_e32 v0, 1.0, v0
	v_rcp_f32_e32 v88, v0
	v_mul_f32_e32 v0, 0xbfb8aa3b, v93
	v_exp_f32_e32 v0, v0
	s_nop 0
	v_add_f32_e32 v0, 1.0, v0
	v_rcp_f32_e32 v89, v0
	v_mul_f32_e32 v0, 0xbfb8aa3b, v94
	v_exp_f32_e32 v0, v0
	v_pk_fma_f32 v[84:85], v[88:89], v[124:125], v[194:195]
	global_store_dwordx4 v[134:135], v[82:85], off offset:64
	v_add_f32_e32 v0, 1.0, v0
	v_rcp_f32_e32 v86, v0
	v_mul_f32_e32 v0, 0xbfb8aa3b, v95
	v_exp_f32_e32 v0, v0
	s_nop 0
	v_add_f32_e32 v0, 1.0, v0
	v_rcp_f32_e32 v87, v0
	v_mul_f32_e32 v0, 0xbfb8aa3b, v96
	v_exp_f32_e32 v0, v0
	v_pk_fma_f32 v[82:83], v[86:87], v[126:127], v[196:197]
	v_add_f32_e32 v0, 1.0, v0
	v_rcp_f32_e32 v88, v0
	v_mul_f32_e32 v0, 0xbfb8aa3b, v97
	v_exp_f32_e32 v0, v0
	s_nop 0
	v_add_f32_e32 v0, 1.0, v0
	v_rcp_f32_e32 v89, v0
	v_mul_f32_e32 v0, 0xbfb8aa3b, v66
	v_exp_f32_e32 v0, v0
	v_pk_fma_f32 v[84:85], v[88:89], v[128:129], v[198:199]
	global_store_dwordx4 v[134:135], v[82:85], off offset:96
	v_add_f32_e32 v0, 1.0, v0
	s_nop 0
	v_rcp_f32_e32 v82, v0
	v_mul_f32_e32 v0, 0xbfb8aa3b, v67
	v_exp_f32_e32 v0, v0
	s_nop 0
	v_add_f32_e32 v0, 1.0, v0
	v_rcp_f32_e32 v83, v0
	v_mul_f32_e32 v0, 0xbfb8aa3b, v68
	v_exp_f32_e32 v0, v0
	s_nop 0
	v_add_f32_e32 v0, 1.0, v0
	v_rcp_f32_e32 v84, v0
	v_mul_f32_e32 v0, 0xbfb8aa3b, v69
	v_exp_f32_e32 v0, v0
	v_pk_fma_f32 v[66:67], v[82:83], v[98:99], v[200:201]
	v_add_f32_e32 v0, 1.0, v0
	v_rcp_f32_e32 v85, v0
	v_mul_f32_e32 v0, 0xbfb8aa3b, v70
	v_exp_f32_e32 v0, v0
	v_pk_fma_f32 v[68:69], v[84:85], v[100:101], v[202:203]
	global_store_dwordx4 v[134:135], v[66:69], off offset:128
	v_add_f32_e32 v0, 1.0, v0
	v_rcp_f32_e32 v70, v0
	v_mul_f32_e32 v0, 0xbfb8aa3b, v71
	v_exp_f32_e32 v0, v0
	s_nop 0
	v_add_f32_e32 v0, 1.0, v0
	v_rcp_f32_e32 v71, v0
	v_mul_f32_e32 v0, 0xbfb8aa3b, v72
	v_exp_f32_e32 v0, v0
	v_pk_fma_f32 v[66:67], v[70:71], v[102:103], v[204:205]
	v_add_f32_e32 v0, 1.0, v0
	v_rcp_f32_e32 v72, v0
	v_mul_f32_e32 v0, 0xbfb8aa3b, v73
	v_exp_f32_e32 v0, v0
	s_nop 0
	v_add_f32_e32 v0, 1.0, v0
	v_rcp_f32_e32 v73, v0
	v_mul_f32_e32 v0, 0xbfb8aa3b, v74
	v_exp_f32_e32 v0, v0
	v_pk_fma_f32 v[68:69], v[72:73], v[104:105], v[206:207]
	global_store_dwordx4 v[134:135], v[66:69], off offset:160
	v_add_f32_e32 v0, 1.0, v0
	v_rcp_f32_e32 v70, v0
	v_mul_f32_e32 v0, 0xbfb8aa3b, v75
	v_exp_f32_e32 v0, v0
	s_nop 0
	v_add_f32_e32 v0, 1.0, v0
	v_rcp_f32_e32 v71, v0
	v_mul_f32_e32 v0, 0xbfb8aa3b, v76
	v_exp_f32_e32 v0, v0
	s_waitcnt vmcnt(13)
; DI float sigmoidf_(float x) { return __builtin_amdgcn_rcpf(1.f + __expf(-x)); }
; DI void phase_ple(const bf16_t* __restrict__ Nb, const bf16_t* __restrict__ PB, const bf16_t* __restrict__ PG,
;                           const bf16_t* __restrict__ PP, float* __restrict__ x, char* lds) {
;     ...
;         float* xp = x + (size_t)(mt * 128 + 64 * wm + 32 * mi + l31) * 1024 + nt * 128 + 64 * wn + 32 * ni + 4 * h2;
;         float4 xs[4];
; #pragma unroll
;         for (int g = 0; g < 4; ++g) xs[g] = *(const float4*)(xp + 8 * g);
; #pragma unroll
;         for (int g = 0; g < 4; ++g) {
;           float4 o;
;           o.x = xs[g].x + sigmoidf_(a0[mi][ni][4 * g]) * a1[mi][ni][4 * g];
;           o.y = xs[g].y + sigmoidf_(a0[mi][ni][4 * g + 1]) * a1[mi][ni][4 * g + 1];
;           o.z = xs[g].z + sigmoidf_(a0[mi][ni][4 * g + 2]) * a1[mi][ni][4 * g + 2];
;           o.w = xs[g].w + sigmoidf_(a0[mi][ni][4 * g + 3]) * a1[mi][ni][4 * g + 3];
;           *(float4*)(xp + 8 * g) = o;
	v_pk_fma_f32 v[66:67], v[70:71], v[106:107], v[154:155]
	v_add_f32_e32 v0, 1.0, v0
	v_rcp_f32_e32 v72, v0
	v_mul_f32_e32 v0, 0xbfb8aa3b, v77
	v_exp_f32_e32 v0, v0
	s_nop 0
	v_add_f32_e32 v0, 1.0, v0
	v_rcp_f32_e32 v73, v0
	v_mul_f32_e32 v0, 0xbfb8aa3b, v78
	v_exp_f32_e32 v0, v0
	v_pk_fma_f32 v[68:69], v[72:73], v[108:109], v[156:157]
	v_add_f32_e32 v0, 1.0, v0
	global_store_dwordx4 v[134:135], v[66:69], off offset:192
	s_nop 1
	v_rcp_f32_e32 v66, v0
	v_mul_f32_e32 v0, 0xbfb8aa3b, v79
	v_exp_f32_e32 v0, v0
	s_nop 0
	v_add_f32_e32 v0, 1.0, v0
	v_rcp_f32_e32 v67, v0
	v_mul_f32_e32 v0, 0xbfb8aa3b, v80
	v_exp_f32_e32 v0, v0
	s_waitcnt vmcnt(13)
	v_pk_fma_f32 v[66:67], v[66:67], v[110:111], v[158:159]
	v_add_f32_e32 v0, 1.0, v0
	v_rcp_f32_e32 v68, v0
	v_mul_f32_e32 v0, 0xbfb8aa3b, v81
	v_exp_f32_e32 v0, v0
	s_nop 0
	v_add_f32_e32 v0, 1.0, v0
	v_rcp_f32_e32 v69, v0
	v_mul_f32_e32 v0, 0xbfb8aa3b, v34
	v_exp_f32_e32 v0, v0
	v_pk_fma_f32 v[68:69], v[68:69], v[112:113], v[160:161]
	global_store_dwordx4 v[134:135], v[66:69], off offset:224
	v_add_f32_e32 v0, 1.0, v0
	s_nop 0
	v_rcp_f32_e32 v68, v0
	v_mul_f32_e32 v0, 0xbfb8aa3b, v35
	v_exp_f32_e32 v0, v0
	v_or_b32_e32 v66, 32, v132
	v_ashrrev_i32_e32 v67, 31, v66
	v_lshlrev_b64 v[66:67], 12, v[66:67]
	v_add_f32_e32 v0, 1.0, v0
	v_rcp_f32_e32 v69, v0
	v_mul_f32_e32 v0, 0xbfb8aa3b, v36
	v_exp_f32_e32 v0, v0
	v_lshl_add_u64 v[66:67], v[130:131], 0, v[66:67]
	v_add_f32_e32 v0, 1.0, v0
	v_rcp_f32_e32 v70, v0
	v_mul_f32_e32 v0, 0xbfb8aa3b, v37
	v_exp_f32_e32 v0, v0
	s_waitcnt vmcnt(13)
	v_pk_fma_f32 v[34:35], v[68:69], v[50:51], v[162:163]
	v_add_f32_e32 v0, 1.0, v0
	v_rcp_f32_e32 v71, v0
	v_mul_f32_e32 v0, 0xbfb8aa3b, v38
	v_exp_f32_e32 v0, v0
	v_pk_fma_f32 v[36:37], v[70:71], v[52:53], v[164:165]
	global_store_dwordx4 v[66:67], v[34:37], off
	v_add_f32_e32 v0, 1.0, v0
	v_rcp_f32_e32 v38, v0
	v_mul_f32_e32 v0, 0xbfb8aa3b, v39
	v_exp_f32_e32 v0, v0
	s_nop 0
	v_add_f32_e32 v0, 1.0, v0
	v_rcp_f32_e32 v39, v0
	v_mul_f32_e32 v0, 0xbfb8aa3b, v40
	v_exp_f32_e32 v0, v0
	s_waitcnt vmcnt(13)
	v_pk_fma_f32 v[34:35], v[38:39], v[54:55], v[166:167]
	v_add_f32_e32 v0, 1.0, v0
	v_rcp_f32_e32 v40, v0
	v_mul_f32_e32 v0, 0xbfb8aa3b, v41
	v_exp_f32_e32 v0, v0
	s_nop 0
	v_add_f32_e32 v0, 1.0, v0
	v_rcp_f32_e32 v41, v0
	v_mul_f32_e32 v0, 0xbfb8aa3b, v42
	v_exp_f32_e32 v0, v0
	v_pk_fma_f32 v[36:37], v[40:41], v[56:57], v[168:169]
	global_store_dwordx4 v[66:67], v[34:37], off offset:32
	v_add_f32_e32 v0, 1.0, v0
	v_rcp_f32_e32 v38, v0
	v_mul_f32_e32 v0, 0xbfb8aa3b, v43
	v_exp_f32_e32 v0, v0
	s_nop 0
	v_add_f32_e32 v0, 1.0, v0
	v_rcp_f32_e32 v39, v0
	v_mul_f32_e32 v0, 0xbfb8aa3b, v44
	v_exp_f32_e32 v0, v0
	s_waitcnt vmcnt(13)
	v_pk_fma_f32 v[34:35], v[38:39], v[58:59], v[170:171]
	v_add_f32_e32 v0, 1.0, v0
	v_rcp_f32_e32 v40, v0
	v_mul_f32_e32 v0, 0xbfb8aa3b, v45
	v_exp_f32_e32 v0, v0
	s_nop 0
	v_add_f32_e32 v0, 1.0, v0
	v_rcp_f32_e32 v41, v0
	v_mul_f32_e32 v0, 0xbfb8aa3b, v46
	v_exp_f32_e32 v0, v0
	v_pk_fma_f32 v[36:37], v[40:41], v[60:61], v[172:173]
	global_store_dwordx4 v[66:67], v[34:37], off offset:64
	v_add_f32_e32 v0, 1.0, v0
	v_rcp_f32_e32 v38, v0
	v_mul_f32_e32 v0, 0xbfb8aa3b, v47
	v_exp_f32_e32 v0, v0
	s_nop 0
	v_add_f32_e32 v0, 1.0, v0
	v_rcp_f32_e32 v39, v0
	v_mul_f32_e32 v0, 0xbfb8aa3b, v48
	v_exp_f32_e32 v0, v0
	s_waitcnt vmcnt(13)
	v_pk_fma_f32 v[34:35], v[38:39], v[62:63], v[174:175]
	v_add_f32_e32 v0, 1.0, v0
	v_rcp_f32_e32 v40, v0
	v_mul_f32_e32 v0, 0xbfb8aa3b, v49
	v_exp_f32_e32 v0, v0
	s_nop 0
	v_add_f32_e32 v0, 1.0, v0
	v_rcp_f32_e32 v41, v0
	v_mul_f32_e32 v0, 0xbfb8aa3b, v2
	v_exp_f32_e32 v0, v0
	v_pk_fma_f32 v[36:37], v[40:41], v[64:65], v[176:177]
	global_store_dwordx4 v[66:67], v[34:37], off offset:96
	v_add_f32_e32 v0, 1.0, v0
	s_nop 0
	v_rcp_f32_e32 v34, v0
	v_mul_f32_e32 v0, 0xbfb8aa3b, v3
	v_exp_f32_e32 v0, v0
	s_nop 0
	v_add_f32_e32 v0, 1.0, v0
	v_rcp_f32_e32 v35, v0
	v_mul_f32_e32 v0, 0xbfb8aa3b, v4
	v_exp_f32_e32 v0, v0
	s_nop 0
	v_add_f32_e32 v0, 1.0, v0
	v_rcp_f32_e32 v36, v0
	v_mul_f32_e32 v0, 0xbfb8aa3b, v5
	v_exp_f32_e32 v0, v0
	s_waitcnt vmcnt(13)
	v_pk_fma_f32 v[2:3], v[34:35], v[18:19], v[178:179]
	v_add_f32_e32 v0, 1.0, v0
	v_rcp_f32_e32 v37, v0
	v_mul_f32_e32 v0, 0xbfb8aa3b, v6
	v_exp_f32_e32 v0, v0
	v_pk_fma_f32 v[4:5], v[36:37], v[20:21], v[180:181]
	global_store_dwordx4 v[66:67], v[2:5], off offset:128
	v_add_f32_e32 v0, 1.0, v0
	v_rcp_f32_e32 v6, v0
	v_mul_f32_e32 v0, 0xbfb8aa3b, v7
	v_exp_f32_e32 v0, v0
	s_nop 0
	v_add_f32_e32 v0, 1.0, v0
	v_rcp_f32_e32 v7, v0
	v_mul_f32_e32 v0, 0xbfb8aa3b, v8
	v_exp_f32_e32 v0, v0
	s_waitcnt vmcnt(13)
	v_pk_fma_f32 v[2:3], v[6:7], v[22:23], v[142:143]
	v_add_f32_e32 v0, 1.0, v0
	v_rcp_f32_e32 v8, v0
	v_mul_f32_e32 v0, 0xbfb8aa3b, v9
	v_exp_f32_e32 v0, v0
	s_nop 0
	v_add_f32_e32 v0, 1.0, v0
	v_rcp_f32_e32 v9, v0
	v_mul_f32_e32 v0, 0xbfb8aa3b, v10
	v_exp_f32_e32 v0, v0
	v_pk_fma_f32 v[4:5], v[8:9], v[24:25], v[144:145]
	global_store_dwordx4 v[66:67], v[2:5], off offset:160
	global_load_dwordx4 v[2:5], v[66:67], off offset:192
	v_add_f32_e32 v0, 1.0, v0
	v_rcp_f32_e32 v6, v0
	v_mul_f32_e32 v0, 0xbfb8aa3b, v11
	v_exp_f32_e32 v0, v0
	s_nop 0
	v_add_f32_e32 v0, 1.0, v0
	v_rcp_f32_e32 v7, v0
	v_mul_f32_e32 v0, 0xbfb8aa3b, v12
	v_exp_f32_e32 v0, v0
	s_waitcnt vmcnt(0)
	v_pk_fma_f32 v[2:3], v[6:7], v[26:27], v[2:3]
	v_add_f32_e32 v0, 1.0, v0
	v_rcp_f32_e32 v8, v0
	v_mul_f32_e32 v0, 0xbfb8aa3b, v13
	v_exp_f32_e32 v0, v0
	s_nop 0
	v_add_f32_e32 v0, 1.0, v0
	v_rcp_f32_e32 v9, v0
	v_mul_f32_e32 v0, 0xbfb8aa3b, v14
	v_exp_f32_e32 v0, v0
	v_pk_fma_f32 v[4:5], v[8:9], v[28:29], v[4:5]
	global_store_dwordx4 v[66:67], v[2:5], off offset:192
	global_load_dwordx4 v[2:5], v[66:67], off offset:224
	v_add_f32_e32 v0, 1.0, v0
	v_rcp_f32_e32 v6, v0
	v_mul_f32_e32 v0, 0xbfb8aa3b, v15
	v_exp_f32_e32 v0, v0
	s_nop 0
	v_add_f32_e32 v0, 1.0, v0
	v_rcp_f32_e32 v7, v0
	v_mul_f32_e32 v0, 0xbfb8aa3b, v16
	v_exp_f32_e32 v0, v0
	s_waitcnt vmcnt(0)
	v_pk_fma_f32 v[2:3], v[6:7], v[30:31], v[2:3]
	v_add_f32_e32 v0, 1.0, v0
	v_rcp_f32_e32 v8, v0
	v_mul_f32_e32 v0, 0xbfb8aa3b, v17
	v_exp_f32_e32 v0, v0
	s_nop 0
	v_add_f32_e32 v0, 1.0, v0
	v_rcp_f32_e32 v9, v0
	s_nop 0
	v_pk_fma_f32 v[4:5], v[8:9], v[32:33], v[4:5]
	global_store_dwordx4 v[66:67], v[2:5], off offset:224
	s_cbranch_scc0 .LBB0_1291
